# B1: hand-written qkv epilogue (hoisted loads, counted waits) + SA(0,0) LDS-DMA stage moved from phase 2 to phase 3 (pieces 2/4/4/6)
# speedup vs baseline: 1.0050x; 1.0050x over previous
.LBB0_156:
	s_add_u32 s6, s0, 0xfffc0080
	s_addc_u32 s7, s1, -1
	s_add_i32 s50, 16, 0x10000
	s_cmp_eq_u32 s49, 12
	s_cselect_b32 s9, s3, s7
	s_cselect_b32 s8, s23, s6
	v_add_u32_e32 v151, s50, v176
	s_cselect_b32 s7, s21, s42
	s_cselect_b32 s6, s28, s29
	s_add_i32 s52, 16, 0x14000
	ds_read_b128 v[132:135], v151
	ds_read_b128 v[152:155], v151 offset:1024
	ds_read_b128 v[156:159], v151 offset:2048
	ds_read_b128 v[160:163], v151 offset:3072
	v_add_u32_e32 v151, s52, v176
	ds_read_b128 v[164:167], v151
	ds_read_b128 v[168:171], v151 offset:1024
	ds_read_b128 v[172:175], v151 offset:2048
	ds_read_b128 v[180:183], v151 offset:3072
	v_lshl_add_u64 v[216:217], s[0:1], 0, v[146:147]
	s_add_i32 m0, s37, 0xc000
	ds_read_b128 v[184:187], v178
	ds_read_b128 v[188:191], v178 offset:1024
	ds_read_b128 v[192:195], v178 offset:2048
	ds_read_b128 v[196:199], v178 offset:3072
	ds_read_b128 v[200:203], v178 offset:4096
	ds_read_b128 v[204:207], v178 offset:5120
	ds_read_b128 v[208:211], v178 offset:6144
	ds_read_b128 v[212:215], v178 offset:7168
	global_load_lds_dwordx4 v[216:217], off
	v_lshl_add_u64 v[216:217], s[0:1], 0, v[148:149]
	s_add_i32 m0, s37, 0xe000
	s_nop 0
	global_load_lds_dwordx4 v[216:217], off
	s_waitcnt vmcnt(8)
	s_waitcnt lgkmcnt(0)
	s_barrier
	s_setprio 1
	s_waitcnt lgkmcnt(0)
	v_mfma_f32_16x16x32_bf16 v[128:131], v[132:135], v[184:187], v[128:131]
	v_mfma_f32_16x16x32_bf16 v[124:127], v[156:159], v[184:187], v[124:127]
	v_mfma_f32_16x16x32_bf16 v[112:115], v[132:135], v[192:195], v[112:115]
	v_mfma_f32_16x16x32_bf16 v[108:111], v[156:159], v[192:195], v[108:111]
	v_mfma_f32_16x16x32_bf16 v[96:99], v[132:135], v[200:203], v[96:99]
	v_mfma_f32_16x16x32_bf16 v[92:95], v[156:159], v[200:203], v[92:95]
	v_mfma_f32_16x16x32_bf16 v[80:83], v[132:135], v[208:211], v[80:83]
	v_mfma_f32_16x16x32_bf16 v[76:79], v[156:159], v[208:211], v[76:79]
	v_mfma_f32_16x16x32_bf16 v[128:131], v[152:155], v[188:191], v[128:131]
	v_mfma_f32_16x16x32_bf16 v[124:127], v[160:163], v[188:191], v[124:127]
	v_mfma_f32_16x16x32_bf16 v[112:115], v[152:155], v[196:199], v[112:115]
	v_mfma_f32_16x16x32_bf16 v[108:111], v[160:163], v[196:199], v[108:111]
	v_mfma_f32_16x16x32_bf16 v[96:99], v[152:155], v[204:207], v[96:99]
	v_mfma_f32_16x16x32_bf16 v[92:95], v[160:163], v[204:207], v[92:95]
	v_mfma_f32_16x16x32_bf16 v[80:83], v[152:155], v[212:215], v[80:83]
	v_mfma_f32_16x16x32_bf16 v[76:79], v[160:163], v[212:215], v[76:79]
	s_setprio 0
	s_setprio 1
	v_mfma_f32_16x16x32_bf16 v[120:123], v[164:167], v[184:187], v[120:123]
	v_mfma_f32_16x16x32_bf16 v[116:119], v[172:175], v[184:187], v[116:119]
	v_mfma_f32_16x16x32_bf16 v[104:107], v[164:167], v[192:195], v[104:107]
	v_mfma_f32_16x16x32_bf16 v[100:103], v[172:175], v[192:195], v[100:103]
	v_mfma_f32_16x16x32_bf16 v[88:91], v[164:167], v[200:203], v[88:91]
	v_mfma_f32_16x16x32_bf16 v[84:87], v[172:175], v[200:203], v[84:87]
	v_mfma_f32_16x16x32_bf16 v[72:75], v[164:167], v[208:211], v[72:75]
	v_mfma_f32_16x16x32_bf16 v[68:71], v[172:175], v[208:211], v[68:71]
	v_mfma_f32_16x16x32_bf16 v[120:123], v[168:171], v[188:191], v[120:123]
	v_mfma_f32_16x16x32_bf16 v[116:119], v[180:183], v[188:191], v[116:119]
	v_mfma_f32_16x16x32_bf16 v[104:107], v[168:171], v[196:199], v[104:107]
	v_mfma_f32_16x16x32_bf16 v[100:103], v[180:183], v[196:199], v[100:103]
	v_mfma_f32_16x16x32_bf16 v[88:91], v[168:171], v[204:207], v[88:91]
	v_mfma_f32_16x16x32_bf16 v[84:87], v[180:183], v[204:207], v[84:87]
	v_mfma_f32_16x16x32_bf16 v[72:75], v[168:171], v[212:215], v[72:75]
	v_mfma_f32_16x16x32_bf16 v[68:71], v[180:183], v[212:215], v[68:71]
	s_setprio 0
	s_barrier
	s_add_i32 s50, s50, s36
	v_lshl_add_u64 v[216:217], s[6:7], 0, v[138:139]
	s_mov_b32 m0, s50
	ds_read_b128 v[184:187], v178 offset:16384
	ds_read_b128 v[188:191], v178 offset:17408
	ds_read_b128 v[192:195], v178 offset:18432
	ds_read_b128 v[196:199], v178 offset:19456
	ds_read_b128 v[200:203], v178 offset:20480
	ds_read_b128 v[204:207], v178 offset:21504
	ds_read_b128 v[208:211], v178 offset:22528
	ds_read_b128 v[212:215], v178 offset:23552
	global_load_lds_dwordx4 v[216:217], off
	s_add_i32 m0, s50, 0x2000
	s_add_u32 s50, s6, 0x40000
	v_lshl_add_u64 v[218:219], s[6:7], 0, v[0:1]
	s_addc_u32 s51, s7, 0
	s_add_i32 s52, s52, s36
	global_load_lds_dwordx4 v[218:219], off
	v_lshl_add_u64 v[220:221], s[50:51], 0, v[138:139]
	s_mov_b32 m0, s52
	v_lshl_add_u64 v[224:225], s[8:9], 0, v[136:137]
	global_load_lds_dwordx4 v[220:221], off
	v_lshl_add_u64 v[220:221], s[50:51], 0, v[0:1]
	s_add_i32 m0, s52, 0x2000
	s_nop 0
	global_load_lds_dwordx4 v[220:221], off
	v_lshl_add_u64 v[220:221], s[8:9], 0, v[140:141]
	s_waitcnt vmcnt(6)
	s_waitcnt lgkmcnt(0)
	s_barrier
	s_setprio 1
	s_waitcnt lgkmcnt(0)
	v_mfma_f32_16x16x32_bf16 v[64:67], v[132:135], v[184:187], v[64:67]
	v_mfma_f32_16x16x32_bf16 v[60:63], v[156:159], v[184:187], v[60:63]
	v_mfma_f32_16x16x32_bf16 v[48:51], v[132:135], v[192:195], v[48:51]
	v_mfma_f32_16x16x32_bf16 v[44:47], v[156:159], v[192:195], v[44:47]
	v_mfma_f32_16x16x32_bf16 v[32:35], v[132:135], v[200:203], v[32:35]
	v_mfma_f32_16x16x32_bf16 v[28:31], v[156:159], v[200:203], v[28:31]
	v_mfma_f32_16x16x32_bf16 v[16:19], v[132:135], v[208:211], v[16:19]
	v_mfma_f32_16x16x32_bf16 v[12:15], v[156:159], v[208:211], v[12:15]
	v_mfma_f32_16x16x32_bf16 v[64:67], v[152:155], v[188:191], v[64:67]
	v_mfma_f32_16x16x32_bf16 v[60:63], v[160:163], v[188:191], v[60:63]
	v_mfma_f32_16x16x32_bf16 v[48:51], v[152:155], v[196:199], v[48:51]
	v_mfma_f32_16x16x32_bf16 v[44:47], v[160:163], v[196:199], v[44:47]
	v_mfma_f32_16x16x32_bf16 v[32:35], v[152:155], v[204:207], v[32:35]
	v_mfma_f32_16x16x32_bf16 v[28:31], v[160:163], v[204:207], v[28:31]
	v_mfma_f32_16x16x32_bf16 v[16:19], v[152:155], v[212:215], v[16:19]
	v_mfma_f32_16x16x32_bf16 v[12:15], v[160:163], v[212:215], v[12:15]
	s_setprio 0
	s_setprio 1
	v_mfma_f32_16x16x32_bf16 v[56:59], v[164:167], v[184:187], v[56:59]
	v_mfma_f32_16x16x32_bf16 v[52:55], v[172:175], v[184:187], v[52:55]
	v_mfma_f32_16x16x32_bf16 v[40:43], v[164:167], v[192:195], v[40:43]
	v_mfma_f32_16x16x32_bf16 v[36:39], v[172:175], v[192:195], v[36:39]
	v_mfma_f32_16x16x32_bf16 v[24:27], v[164:167], v[200:203], v[24:27]
	v_mfma_f32_16x16x32_bf16 v[20:23], v[172:175], v[200:203], v[20:23]
	v_mfma_f32_16x16x32_bf16 v[8:11], v[164:167], v[208:211], v[8:11]
	v_mfma_f32_16x16x32_bf16 v[4:7], v[172:175], v[208:211], v[4:7]
	v_mfma_f32_16x16x32_bf16 v[56:59], v[168:171], v[188:191], v[56:59]
	v_mfma_f32_16x16x32_bf16 v[52:55], v[180:183], v[188:191], v[52:55]
	v_mfma_f32_16x16x32_bf16 v[40:43], v[168:171], v[196:199], v[40:43]
	v_mfma_f32_16x16x32_bf16 v[36:39], v[180:183], v[196:199], v[36:39]
	v_mfma_f32_16x16x32_bf16 v[24:27], v[168:171], v[204:207], v[24:27]
	v_mfma_f32_16x16x32_bf16 v[20:23], v[180:183], v[204:207], v[20:23]
	v_mfma_f32_16x16x32_bf16 v[8:11], v[168:171], v[212:215], v[8:11]
	v_mfma_f32_16x16x32_bf16 v[4:7], v[180:183], v[212:215], v[4:7]
	s_setprio 0
	s_barrier
	s_add_i32 s50, 16, 0x18000
	v_add_u32_e32 v151, s50, v176
	s_add_i32 s51, 16, 0x1c000
	ds_read_b128 v[132:135], v151
	ds_read_b128 v[152:155], v151 offset:1024
	ds_read_b128 v[156:159], v151 offset:2048
	ds_read_b128 v[160:163], v151 offset:3072
	v_add_u32_e32 v151, s51, v176
	ds_read_b128 v[164:167], v151
	ds_read_b128 v[168:171], v151 offset:1024
	ds_read_b128 v[172:175], v151 offset:2048
	ds_read_b128 v[180:183], v151 offset:3072
	s_mov_b32 m0, s37
	s_nop 0
	global_load_lds_dwordx4 v[220:221], off
	s_mov_b32 m0, s38
	s_nop 0
	global_load_lds_dwordx4 v[224:225], off
	s_add_u32 s8, s8, 0x40000
	s_addc_u32 s9, s9, 0
	s_mov_b32 m0, s39
	v_lshl_add_u64 v[226:227], s[8:9], 0, v[140:141]
	ds_read_b128 v[184:187], v178 offset:32768
	ds_read_b128 v[188:191], v178 offset:33792
	ds_read_b128 v[192:195], v178 offset:34816
	ds_read_b128 v[196:199], v178 offset:35840
	ds_read_b128 v[200:203], v178 offset:36864
	ds_read_b128 v[204:207], v178 offset:37888
	ds_read_b128 v[208:211], v178 offset:38912
	ds_read_b128 v[212:215], v178 offset:39936
	global_load_lds_dwordx4 v[226:227], off
	v_lshl_add_u64 v[226:227], s[8:9], 0, v[136:137]
	s_mov_b32 m0, s40
	s_nop 0
	global_load_lds_dwordx4 v[226:227], off
	s_waitcnt vmcnt(8)
	s_waitcnt lgkmcnt(0)
	s_barrier
	s_setprio 1
	s_waitcnt lgkmcnt(0)
	v_mfma_f32_16x16x32_bf16 v[128:131], v[132:135], v[184:187], v[128:131]
	v_mfma_f32_16x16x32_bf16 v[124:127], v[156:159], v[184:187], v[124:127]
	v_mfma_f32_16x16x32_bf16 v[112:115], v[132:135], v[192:195], v[112:115]
	v_mfma_f32_16x16x32_bf16 v[108:111], v[156:159], v[192:195], v[108:111]
	v_mfma_f32_16x16x32_bf16 v[96:99], v[132:135], v[200:203], v[96:99]
	v_mfma_f32_16x16x32_bf16 v[92:95], v[156:159], v[200:203], v[92:95]
	v_mfma_f32_16x16x32_bf16 v[80:83], v[132:135], v[208:211], v[80:83]
	v_mfma_f32_16x16x32_bf16 v[76:79], v[156:159], v[208:211], v[76:79]
	v_mfma_f32_16x16x32_bf16 v[128:131], v[152:155], v[188:191], v[128:131]
	v_mfma_f32_16x16x32_bf16 v[124:127], v[160:163], v[188:191], v[124:127]
	v_mfma_f32_16x16x32_bf16 v[112:115], v[152:155], v[196:199], v[112:115]
	v_mfma_f32_16x16x32_bf16 v[108:111], v[160:163], v[196:199], v[108:111]
	v_mfma_f32_16x16x32_bf16 v[96:99], v[152:155], v[204:207], v[96:99]
	v_mfma_f32_16x16x32_bf16 v[92:95], v[160:163], v[204:207], v[92:95]
	v_mfma_f32_16x16x32_bf16 v[80:83], v[152:155], v[212:215], v[80:83]
	v_mfma_f32_16x16x32_bf16 v[76:79], v[160:163], v[212:215], v[76:79]
	s_setprio 0
	s_setprio 1
	v_mfma_f32_16x16x32_bf16 v[120:123], v[164:167], v[184:187], v[120:123]
	v_mfma_f32_16x16x32_bf16 v[116:119], v[172:175], v[184:187], v[116:119]
	v_mfma_f32_16x16x32_bf16 v[104:107], v[164:167], v[192:195], v[104:107]
	v_mfma_f32_16x16x32_bf16 v[100:103], v[172:175], v[192:195], v[100:103]
	v_mfma_f32_16x16x32_bf16 v[88:91], v[164:167], v[200:203], v[88:91]
	v_mfma_f32_16x16x32_bf16 v[84:87], v[172:175], v[200:203], v[84:87]
	v_mfma_f32_16x16x32_bf16 v[72:75], v[164:167], v[208:211], v[72:75]
	v_mfma_f32_16x16x32_bf16 v[68:71], v[172:175], v[208:211], v[68:71]
	v_mfma_f32_16x16x32_bf16 v[120:123], v[168:171], v[188:191], v[120:123]
	v_mfma_f32_16x16x32_bf16 v[116:119], v[180:183], v[188:191], v[116:119]
	v_mfma_f32_16x16x32_bf16 v[104:107], v[168:171], v[196:199], v[104:107]
	v_mfma_f32_16x16x32_bf16 v[100:103], v[180:183], v[196:199], v[100:103]
	v_mfma_f32_16x16x32_bf16 v[88:91], v[168:171], v[204:207], v[88:91]
	v_mfma_f32_16x16x32_bf16 v[84:87], v[180:183], v[204:207], v[84:87]
	v_mfma_f32_16x16x32_bf16 v[72:75], v[168:171], v[212:215], v[72:75]
	v_mfma_f32_16x16x32_bf16 v[68:71], v[180:183], v[212:215], v[68:71]
	s_setprio 0
	s_barrier
	s_add_i32 s8, s50, s36
	v_lshl_add_u64 v[216:217], v[216:217], 0, s[84:85]
	s_mov_b32 m0, s8
	ds_read_b128 v[184:187], v178 offset:49152
	ds_read_b128 v[188:191], v178 offset:50176
	ds_read_b128 v[192:195], v178 offset:51200
	ds_read_b128 v[196:199], v178 offset:52224
	ds_read_b128 v[200:203], v178 offset:53248
	ds_read_b128 v[204:207], v178 offset:54272
	ds_read_b128 v[208:211], v178 offset:55296
	ds_read_b128 v[212:215], v178 offset:56320
	global_load_lds_dwordx4 v[216:217], off
	s_add_i32 m0, s8, 0x2000
	s_add_u32 s6, s6, 0x40080
	v_lshl_add_u64 v[216:217], v[218:219], 0, s[84:85]
	s_addc_u32 s7, s7, 0
	s_add_i32 s8, s51, s36
	global_load_lds_dwordx4 v[216:217], off
	v_lshl_add_u64 v[216:217], s[6:7], 0, v[138:139]
	s_mov_b32 m0, s8
	s_nop 0
	global_load_lds_dwordx4 v[216:217], off
	v_lshl_add_u64 v[216:217], s[6:7], 0, v[0:1]
	s_add_i32 m0, s8, 0x2000
	s_nop 0
	global_load_lds_dwordx4 v[216:217], off
	v_lshl_add_u64 v[216:217], v[220:221], 0, s[84:85]
	s_mov_b32 m0, s44
	s_nop 0
	global_load_lds_dwordx4 v[216:217], off
	v_lshl_add_u64 v[216:217], v[224:225], 0, s[84:85]
	s_mov_b32 m0, s45
	s_nop 0
	global_load_lds_dwordx4 v[216:217], off
	s_waitcnt vmcnt(8)
	s_waitcnt lgkmcnt(0)
	s_barrier
	s_setprio 1
	s_waitcnt lgkmcnt(0)
	v_mfma_f32_16x16x32_bf16 v[64:67], v[132:135], v[184:187], v[64:67]
	v_mfma_f32_16x16x32_bf16 v[60:63], v[156:159], v[184:187], v[60:63]
	v_mfma_f32_16x16x32_bf16 v[48:51], v[132:135], v[192:195], v[48:51]
	v_mfma_f32_16x16x32_bf16 v[44:47], v[156:159], v[192:195], v[44:47]
	v_mfma_f32_16x16x32_bf16 v[32:35], v[132:135], v[200:203], v[32:35]
	v_mfma_f32_16x16x32_bf16 v[28:31], v[156:159], v[200:203], v[28:31]
	v_mfma_f32_16x16x32_bf16 v[16:19], v[132:135], v[208:211], v[16:19]
	v_mfma_f32_16x16x32_bf16 v[12:15], v[156:159], v[208:211], v[12:15]
	v_mfma_f32_16x16x32_bf16 v[64:67], v[152:155], v[188:191], v[64:67]
	v_mfma_f32_16x16x32_bf16 v[60:63], v[160:163], v[188:191], v[60:63]
	v_mfma_f32_16x16x32_bf16 v[48:51], v[152:155], v[196:199], v[48:51]
	v_mfma_f32_16x16x32_bf16 v[44:47], v[160:163], v[196:199], v[44:47]
	v_mfma_f32_16x16x32_bf16 v[32:35], v[152:155], v[204:207], v[32:35]
	v_mfma_f32_16x16x32_bf16 v[28:31], v[160:163], v[204:207], v[28:31]
	v_mfma_f32_16x16x32_bf16 v[16:19], v[152:155], v[212:215], v[16:19]
	v_mfma_f32_16x16x32_bf16 v[12:15], v[160:163], v[212:215], v[12:15]
	s_setprio 0
	s_setprio 1
	v_mfma_f32_16x16x32_bf16 v[56:59], v[164:167], v[184:187], v[56:59]
	v_mfma_f32_16x16x32_bf16 v[52:55], v[172:175], v[184:187], v[52:55]
	v_mfma_f32_16x16x32_bf16 v[40:43], v[164:167], v[192:195], v[40:43]
	v_mfma_f32_16x16x32_bf16 v[36:39], v[172:175], v[192:195], v[36:39]
	v_mfma_f32_16x16x32_bf16 v[24:27], v[164:167], v[200:203], v[24:27]
	v_mfma_f32_16x16x32_bf16 v[20:23], v[172:175], v[200:203], v[20:23]
	v_mfma_f32_16x16x32_bf16 v[8:11], v[164:167], v[208:211], v[8:11]
	v_mfma_f32_16x16x32_bf16 v[4:7], v[172:175], v[208:211], v[4:7]
	v_mfma_f32_16x16x32_bf16 v[56:59], v[168:171], v[188:191], v[56:59]
	v_mfma_f32_16x16x32_bf16 v[52:55], v[180:183], v[188:191], v[52:55]
	v_mfma_f32_16x16x32_bf16 v[40:43], v[168:171], v[196:199], v[40:43]
	v_mfma_f32_16x16x32_bf16 v[36:39], v[180:183], v[196:199], v[36:39]
	v_mfma_f32_16x16x32_bf16 v[24:27], v[168:171], v[204:207], v[24:27]
	v_mfma_f32_16x16x32_bf16 v[20:23], v[180:183], v[204:207], v[20:23]
	v_mfma_f32_16x16x32_bf16 v[8:11], v[168:171], v[212:215], v[8:11]
	v_mfma_f32_16x16x32_bf16 v[4:7], v[180:183], v[212:215], v[4:7]
	s_setprio 0
	s_barrier
	s_add_i32 s49, s49, 2
	s_add_u32 s0, s0, 0x100
	s_addc_u32 s1, s1, 0
	s_add_u32 s29, s29, 0x100
	s_addc_u32 s42, s42, 0
	s_cmp_gt_u32 s49, 13
	s_cbranch_scc0 .LBB0_156
	s_and_b64 vcc, exec, s[18:19]
	s_cbranch_vccz .LBB0_159
	s_barrier
